# weight-conversion transposes: output steps wait only for their LDS reads (the global wait moved next to the optional column-scale load), so stores no longer serialise
# baseline (speedup 1.0000x reference)
; #define LAS __attribute__((address_space(3)))
; #define LDS_WAIT() asm volatile("s_waitcnt lgkmcnt(0)" ::: "memory")
; __device__ __forceinline__ unsigned cvt_pk_bf16(float lo, float hi) { const f32x2 v = {lo, hi}; unsigned r = __builtin_bit_cast(unsigned, __builtin_convertvector(v, bf16x2_t)); asm volatile("" : "+v"(r)); return r; }
; __device__ __forceinline__ void tr_item(const float* W, int ldn, int k0, int n0, const float* ks, const float* ns, bf16_t* WT, size_t dld, int rbase, int rstride, int dcol0, LAS float* scr, int lane) {
;     ...
;     for (int j = 0; j < 4; ++j) { const int n = (lane >> 3) + 8 * j; const LAS float* s = scr + (8 * c) * 33 + n; const float sc = ns ? ns[n] : 1.0f;
;         u32x4 o; o.x = cvt_pk_bf16(s[0 * 33] * sc, s[1 * 33] * sc); o.y = cvt_pk_bf16(s[2 * 33] * sc, s[3 * 33] * sc); o.z = cvt_pk_bf16(s[4 * 33] * sc, s[5 * 33] * sc); o.w = cvt_pk_bf16(s[6 * 33] * sc, s[7 * 33] * sc);
;         *(u32x4*)(WT + (size_t)(rbase + rstride * n) * dld + dcol0 + k0 + 8 * c) = o; }
;     LDS_WAIT(); asm volatile("" ::: "memory");
.LBB0_47:
	ds_read2_b32 v[0:1], v45 offset0:24 offset1:57
	v_add_u32_e32 v4, s2, v5
	v_mul_lo_u32 v11, s21, v4
	s_add_i32 s51, s51, s8
	s_add_i32 s59, s59, s60
	s_waitcnt lgkmcnt(0)
	v_pk_mul_f32 v[0:1], v[6:7], v[0:1] op_sel_hi:[0,1]
	v_cvt_pk_bf16_f32 v8, v0, v1
	ds_read2_b32 v[0:1], v45 offset0:90 offset1:123
	s_cmp_lt_i32 s51, s54
	s_waitcnt lgkmcnt(0)
	v_pk_mul_f32 v[0:1], v[6:7], v[0:1] op_sel_hi:[0,1]
	v_cvt_pk_bf16_f32 v9, v0, v1
	ds_read2_b32 v[0:1], v45 offset0:156 offset1:189
	v_ashrrev_i32_e32 v7, 31, v4
	v_mad_u64_u32 v[4:5], s[2:3], s20, v4, 0
	s_waitcnt lgkmcnt(0)
	v_pk_mul_f32 v[0:1], v[6:7], v[0:1] op_sel_hi:[0,1]
	v_cvt_pk_bf16_f32 v10, v0, v1
	ds_read2_b32 v[0:1], v45 offset0:222 offset1:255
	v_mul_lo_u32 v7, s20, v7
	v_add3_u32 v5, v5, v7, v11
	v_lshl_add_u64 v[2:3], v[4:5], 1, v[2:3]
	s_waitcnt lgkmcnt(0)
	v_pk_mul_f32 v[0:1], v[6:7], v[0:1] op_sel_hi:[0,1]
	v_cvt_pk_bf16_f32 v11, v0, v1
	global_store_dwordx4 v[2:3], v[8:11], off
	s_waitcnt lgkmcnt(0)
	s_cbranch_scc0 .LBB0_7

; #define LAS __attribute__((address_space(3)))
; #define LDS_WAIT() asm volatile("s_waitcnt lgkmcnt(0)" ::: "memory")
; __device__ __forceinline__ unsigned cvt_pk_bf16(float lo, float hi) { const f32x2 v = {lo, hi}; unsigned r = __builtin_bit_cast(unsigned, __builtin_convertvector(v, bf16x2_t)); asm volatile("" : "+v"(r)); return r; }
; __device__ __forceinline__ void tr_item(const float* W, int ldn, int k0, int n0, const float* ks, const float* ns, bf16_t* WT, size_t dld, int rbase, int rstride, int dcol0, LAS float* scr, int lane) {
;     ...
;     for (int i = 0; i < 8; ++i) { const int kk = 8 * i + (lane >> 3); const float s = ks ? ks[k0 + kk] : 1.0f; LAS float* d = scr + kk * 33 + 4 * (lane & 7);
;         d[0] = v[i][0] * s; d[1] = v[i][1] * s; d[2] = v[i][2] * s; d[3] = v[i][3] * s; }
;     LDS_WAIT(); asm volatile("" ::: "memory");
;     const int c = lane & 7;
; #pragma unroll
;     for (int j = 0; j < 4; ++j) { const int n = (lane >> 3) + 8 * j; const LAS float* s = scr + (8 * c) * 33 + n; const float sc = ns ? ns[n] : 1.0f;
;         u32x4 o; o.x = cvt_pk_bf16(s[0 * 33] * sc, s[1 * 33] * sc); o.y = cvt_pk_bf16(s[2 * 33] * sc, s[3 * 33] * sc); o.z = cvt_pk_bf16(s[4 * 33] * sc, s[5 * 33] * sc); o.w = cvt_pk_bf16(s[6 * 33] * sc, s[7 * 33] * sc);
;         *(u32x4*)(WT + (size_t)(rbase + rstride * n) * dld + dcol0 + k0 + 8 * c) = o; }
;     LDS_WAIT(); asm volatile("" ::: "memory");
.LBB0_85:
	v_add_u32_e32 v9, 0x18c0, v47
	ds_write2_b32 v9, v4, v5 offset1:1
	v_add_u32_e32 v4, 0x18c8, v47
	ds_write2_b32 v4, v6, v7 offset1:1
	s_waitcnt vmcnt(0)
	v_pk_mul_f32 v[0:1], v[0:1], v[8:9] op_sel_hi:[1,0]
	v_add_u32_e32 v4, 0x1ce0, v47
	ds_write2_b32 v4, v0, v1 offset1:1
	v_pk_mul_f32 v[0:1], v[2:3], v[8:9] op_sel_hi:[1,0]
	v_add_u32_e32 v2, 0x1ce8, v47
	ds_write2_b32 v2, v0, v1 offset1:1
	s_lshl_b64 s[2:3], s[2:3], 2
	s_waitcnt lgkmcnt(0)
	s_add_u32 s2, s22, s2
	s_addc_u32 s3, s23, s3
	v_cndmask_b32_e64 v0, 0, 1, s[26:27]
	v_mov_b32_e32 v4, 1.0
	v_cmp_ne_u32_e64 s[4:5], 1, v0
	s_andn2_b64 vcc, exec, s[26:27]
	v_lshl_add_u64 v[0:1], v[34:35], 2, s[2:3]
	v_mov_b32_e32 v6, 1.0
	s_cbranch_vccnz .LBB0_87
	global_load_dword v6, v[0:1], off
	s_waitcnt vmcnt(0)
.LBB0_87:
	ds_read2_b32 v[2:3], v45 offset1:33
	v_mul_lo_u32 v5, s61, v34
	v_add_u32_e32 v5, v5, v48
	s_lshl_b64 s[2:3], s[28:29], 1
	s_add_u32 s28, s16, s2
	s_waitcnt lgkmcnt(0)
	v_pk_mul_f32 v[2:3], v[6:7], v[2:3] op_sel_hi:[0,1]
	v_cvt_pk_bf16_f32 v8, v2, v3
	ds_read2_b32 v[2:3], v45 offset0:66 offset1:99
	s_addc_u32 s29, s17, s3
	s_lshl_b64 s[2:3], s[30:31], 1
	s_add_u32 s2, s28, s2
	s_addc_u32 s3, s29, s3
	s_waitcnt lgkmcnt(0)
	v_pk_mul_f32 v[2:3], v[6:7], v[2:3] op_sel_hi:[0,1]
	v_cvt_pk_bf16_f32 v9, v2, v3
	ds_read2_b32 v[2:3], v45 offset0:132 offset1:165
	v_ashrrev_i32_e32 v7, 31, v5
	v_mul_lo_u32 v15, s20, v7
	v_mul_lo_u32 v14, s21, v5
	s_and_b64 vcc, exec, s[4:5]
	s_waitcnt lgkmcnt(0)
	v_pk_mul_f32 v[2:3], v[6:7], v[2:3] op_sel_hi:[0,1]
	v_cvt_pk_bf16_f32 v10, v2, v3
	ds_read2_b32 v[12:13], v45 offset0:198 offset1:231
	v_lshl_add_u64 v[2:3], s[2:3], 0, v[36:37]
	s_waitcnt lgkmcnt(0)
	v_pk_mul_f32 v[6:7], v[6:7], v[12:13] op_sel_hi:[0,1]
	v_cvt_pk_bf16_f32 v11, v6, v7
	v_mad_u64_u32 v[6:7], s[2:3], s20, v5, 0
	v_add3_u32 v7, v7, v15, v14
	v_lshl_add_u64 v[6:7], v[6:7], 1, v[2:3]
	global_store_dwordx4 v[6:7], v[8:11], off
	s_cbranch_vccnz .LBB0_89
	global_load_dword v4, v[0:1], off offset:32
	s_waitcnt vmcnt(0)
.LBB0_89:
	ds_read2_b32 v[6:7], v45 offset0:8 offset1:41
	s_lshl_b32 s2, s61, 3
	s_and_b64 vcc, exec, s[4:5]
	s_waitcnt lgkmcnt(0)
	v_pk_mul_f32 v[6:7], v[4:5], v[6:7] op_sel_hi:[0,1]
	v_cvt_pk_bf16_f32 v8, v6, v7
	ds_read2_b32 v[10:11], v45 offset0:74 offset1:107
	v_mov_b32_e32 v6, 1.0
	s_waitcnt lgkmcnt(0)
	v_pk_mul_f32 v[10:11], v[4:5], v[10:11] op_sel_hi:[0,1]
	v_cvt_pk_bf16_f32 v9, v10, v11
	ds_read2_b32 v[10:11], v45 offset0:140 offset1:173
	v_add_u32_e32 v5, s2, v5
	v_ashrrev_i32_e32 v7, 31, v5
	v_mul_lo_u32 v16, s21, v5
	v_mad_u64_u32 v[14:15], s[28:29], s20, v5, 0
	s_waitcnt lgkmcnt(0)
	v_pk_mul_f32 v[10:11], v[4:5], v[10:11] op_sel_hi:[0,1]
	v_cvt_pk_bf16_f32 v10, v10, v11
	ds_read2_b32 v[12:13], v45 offset0:206 offset1:239
	v_mul_lo_u32 v7, s20, v7
	v_add3_u32 v15, v15, v7, v16
	v_lshl_add_u64 v[14:15], v[14:15], 1, v[2:3]
	s_waitcnt lgkmcnt(0)
	v_pk_mul_f32 v[12:13], v[4:5], v[12:13] op_sel_hi:[0,1]
	v_cvt_pk_bf16_f32 v11, v12, v13
	v_mov_b32_e32 v4, 1.0
	global_store_dwordx4 v[14:15], v[8:11], off
	s_cbranch_vccnz .LBB0_91
	global_load_dword v4, v[0:1], off offset:64
	s_waitcnt vmcnt(0)
.LBB0_91:
	ds_read2_b32 v[8:9], v45 offset0:16 offset1:49
	s_and_b64 vcc, exec, s[4:5]
	s_waitcnt lgkmcnt(0)
	v_pk_mul_f32 v[8:9], v[4:5], v[8:9] op_sel_hi:[0,1]
	v_cvt_pk_bf16_f32 v8, v8, v9
	ds_read2_b32 v[10:11], v45 offset0:82 offset1:115
	s_waitcnt lgkmcnt(0)
	v_pk_mul_f32 v[10:11], v[4:5], v[10:11] op_sel_hi:[0,1]
	v_cvt_pk_bf16_f32 v9, v10, v11
	ds_read2_b32 v[10:11], v45 offset0:148 offset1:181
	v_add_u32_e32 v5, s2, v5
	v_ashrrev_i32_e32 v7, 31, v5
	v_mul_lo_u32 v16, s21, v5
	v_mad_u64_u32 v[14:15], s[28:29], s20, v5, 0
	s_waitcnt lgkmcnt(0)
	v_pk_mul_f32 v[10:11], v[4:5], v[10:11] op_sel_hi:[0,1]
	v_cvt_pk_bf16_f32 v10, v10, v11
	ds_read2_b32 v[12:13], v45 offset0:214 offset1:247
	v_mul_lo_u32 v7, s20, v7
	v_add3_u32 v15, v15, v7, v16
	v_lshl_add_u64 v[14:15], v[14:15], 1, v[2:3]
	s_waitcnt lgkmcnt(0)
	v_pk_mul_f32 v[12:13], v[4:5], v[12:13] op_sel_hi:[0,1]
	v_cvt_pk_bf16_f32 v11, v12, v13
	global_store_dwordx4 v[14:15], v[8:11], off
	s_cbranch_vccnz .LBB0_47
	global_load_dword v6, v[0:1], off offset:96
	s_waitcnt vmcnt(0)
	s_branch .LBB0_47

; #define LAS __attribute__((address_space(3)))
; #define LDS_WAIT() asm volatile("s_waitcnt lgkmcnt(0)" ::: "memory")
; __device__ __forceinline__ unsigned cvt_pk_bf16(float lo, float hi) { const f32x2 v = {lo, hi}; unsigned r = __builtin_bit_cast(unsigned, __builtin_convertvector(v, bf16x2_t)); asm volatile("" : "+v"(r)); return r; }
; __device__ __forceinline__ void tr_item(const float* W, int ldn, int k0, int n0, const float* ks, const float* ns, bf16_t* WT, size_t dld, int rbase, int rstride, int dcol0, LAS float* scr, int lane) {
;     ...
;     for (int j = 0; j < 4; ++j) { const int n = (lane >> 3) + 8 * j; const LAS float* s = scr + (8 * c) * 33 + n; const float sc = ns ? ns[n] : 1.0f;
;         u32x4 o; o.x = cvt_pk_bf16(s[0 * 33] * sc, s[1 * 33] * sc); o.y = cvt_pk_bf16(s[2 * 33] * sc, s[3 * 33] * sc); o.z = cvt_pk_bf16(s[4 * 33] * sc, s[5 * 33] * sc); o.w = cvt_pk_bf16(s[6 * 33] * sc, s[7 * 33] * sc);
;         *(u32x4*)(WT + (size_t)(rbase + rstride * n) * dld + dcol0 + k0 + 8 * c) = o; }
;     LDS_WAIT(); asm volatile("" ::: "memory");
.LBB0_487:
	ds_read2_b32 v[4:5], v45 offset0:24 offset1:57
	s_add_i32 s49, s49, s28
	s_add_i32 s59, s59, s60
	s_cmp_lt_i32 s49, s52
	s_waitcnt lgkmcnt(0)
	v_pk_mul_f32 v[4:5], v[6:7], v[4:5] op_sel_hi:[0,1]
	v_cvt_pk_bf16_f32 v8, v4, v5
	ds_read2_b32 v[4:5], v45 offset0:90 offset1:123
	s_waitcnt lgkmcnt(0)
	v_pk_mul_f32 v[4:5], v[6:7], v[4:5] op_sel_hi:[0,1]
	v_cvt_pk_bf16_f32 v9, v4, v5
	ds_read2_b32 v[4:5], v45 offset0:156 offset1:189
	s_waitcnt lgkmcnt(0)
	v_pk_mul_f32 v[4:5], v[6:7], v[4:5] op_sel_hi:[0,1]
	v_cvt_pk_bf16_f32 v10, v4, v5
	ds_read2_b32 v[4:5], v45 offset0:222 offset1:255
	s_waitcnt lgkmcnt(0)
	v_pk_mul_f32 v[4:5], v[6:7], v[4:5] op_sel_hi:[0,1]
	v_cvt_pk_bf16_f32 v11, v4, v5
	v_add_u32_e32 v4, s2, v7
	v_ashrrev_i32_e32 v5, 31, v4
	v_mul_lo_u32 v6, s12, v5
	v_mul_lo_u32 v7, s13, v4
	v_mad_u64_u32 v[4:5], s[2:3], s12, v4, 0
	v_add3_u32 v5, v5, v6, v7
	v_lshl_add_u64 v[2:3], v[4:5], 1, v[2:3]
	global_store_dwordx4 v[2:3], v[8:11], off
	s_waitcnt lgkmcnt(0)
	s_cbranch_scc0 .LBB0_448

; #define LAS __attribute__((address_space(3)))
; #define LDS_WAIT() asm volatile("s_waitcnt lgkmcnt(0)" ::: "memory")
; __device__ __forceinline__ unsigned cvt_pk_bf16(float lo, float hi) { const f32x2 v = {lo, hi}; unsigned r = __builtin_bit_cast(unsigned, __builtin_convertvector(v, bf16x2_t)); asm volatile("" : "+v"(r)); return r; }
; __device__ __forceinline__ void tr_item(const float* W, int ldn, int k0, int n0, const float* ks, const float* ns, bf16_t* WT, size_t dld, int rbase, int rstride, int dcol0, LAS float* scr, int lane) {
;     ...
;     for (int i = 0; i < 8; ++i) { const int kk = 8 * i + (lane >> 3); const float s = ks ? ks[k0 + kk] : 1.0f; LAS float* d = scr + kk * 33 + 4 * (lane & 7);
;         d[0] = v[i][0] * s; d[1] = v[i][1] * s; d[2] = v[i][2] * s; d[3] = v[i][3] * s; }
;     LDS_WAIT(); asm volatile("" ::: "memory");
;     const int c = lane & 7;
; #pragma unroll
;     for (int j = 0; j < 4; ++j) { const int n = (lane >> 3) + 8 * j; const LAS float* s = scr + (8 * c) * 33 + n; const float sc = ns ? ns[n] : 1.0f;
;         u32x4 o; o.x = cvt_pk_bf16(s[0 * 33] * sc, s[1 * 33] * sc); o.y = cvt_pk_bf16(s[2 * 33] * sc, s[3 * 33] * sc); o.z = cvt_pk_bf16(s[4 * 33] * sc, s[5 * 33] * sc); o.w = cvt_pk_bf16(s[6 * 33] * sc, s[7 * 33] * sc);
;         *(u32x4*)(WT + (size_t)(rbase + rstride * n) * dld + dcol0 + k0 + 8 * c) = o; }
;     LDS_WAIT(); asm volatile("" ::: "memory");
.LBB0_525:
	v_add_u32_e32 v11, 0x18c0, v46
	ds_write2_b32 v11, v6, v7 offset1:1
	v_add_u32_e32 v6, 0x18c8, v46
	ds_write2_b32 v6, v8, v9 offset1:1
	s_waitcnt vmcnt(0)
	v_pk_mul_f32 v[2:3], v[2:3], v[10:11] op_sel_hi:[1,0]
	v_add_u32_e32 v6, 0x1ce0, v46
	ds_write2_b32 v6, v2, v3 offset1:1
	v_pk_mul_f32 v[2:3], v[4:5], v[10:11] op_sel_hi:[1,0]
	v_add_u32_e32 v4, 0x1ce8, v46
	ds_write2_b32 v4, v2, v3 offset1:1
	s_lshl_b64 s[2:3], s[20:21], 2
	s_waitcnt lgkmcnt(0)
	s_add_u32 s2, s14, s2
	s_addc_u32 s3, s15, s3
	v_cndmask_b32_e64 v2, 0, 1, s[18:19]
	v_mov_b32_e32 v6, 1.0
	v_cmp_ne_u32_e64 s[4:5], 1, v2
	s_andn2_b64 vcc, exec, s[18:19]
	v_lshl_add_u64 v[4:5], v[34:35], 2, s[2:3]
	v_mov_b32_e32 v8, 1.0
	s_cbranch_vccnz .LBB0_527
	global_load_dword v8, v[4:5], off
	s_waitcnt vmcnt(0)
.LBB0_527:
	ds_read2_b32 v[10:11], v45 offset1:33
	s_lshl_b64 s[2:3], s[22:23], 1
	s_add_u32 s20, s8, s2
	s_addc_u32 s21, s9, s3
	s_lshl_b64 s[2:3], s[24:25], 1
	s_waitcnt lgkmcnt(0)
	v_pk_mul_f32 v[10:11], v[8:9], v[10:11] op_sel_hi:[0,1]
	v_cvt_pk_bf16_f32 v10, v10, v11
	ds_read2_b32 v[12:13], v45 offset0:66 offset1:99
	v_mul_lo_u32 v7, s62, v34
	s_add_u32 s2, s20, s2
	v_add_u32_e32 v7, v7, v37
	s_addc_u32 s3, s21, s3
	s_waitcnt lgkmcnt(0)
	v_pk_mul_f32 v[12:13], v[8:9], v[12:13] op_sel_hi:[0,1]
	v_cvt_pk_bf16_f32 v11, v12, v13
	ds_read2_b32 v[12:13], v45 offset0:132 offset1:165
	v_lshl_add_u64 v[2:3], s[2:3], 0, v[0:1]
	s_and_b64 vcc, exec, s[4:5]
	s_waitcnt lgkmcnt(0)
	v_pk_mul_f32 v[12:13], v[8:9], v[12:13] op_sel_hi:[0,1]
	v_cvt_pk_bf16_f32 v12, v12, v13
	ds_read2_b32 v[14:15], v45 offset0:198 offset1:231
	s_waitcnt lgkmcnt(0)
	v_pk_mul_f32 v[8:9], v[8:9], v[14:15] op_sel_hi:[0,1]
	v_cvt_pk_bf16_f32 v13, v8, v9
	v_ashrrev_i32_e32 v8, 31, v7
	v_mul_lo_u32 v14, s12, v8
	v_mul_lo_u32 v15, s13, v7
	v_mad_u64_u32 v[8:9], s[2:3], s12, v7, 0
	v_add3_u32 v9, v9, v14, v15
	v_lshl_add_u64 v[8:9], v[8:9], 1, v[2:3]
	global_store_dwordx4 v[8:9], v[10:13], off
	s_cbranch_vccnz .LBB0_529
	global_load_dword v6, v[4:5], off offset:32
	s_waitcnt vmcnt(0)
.LBB0_529:
	ds_read2_b32 v[8:9], v45 offset0:8 offset1:41
	s_lshl_b32 s2, s62, 3
	s_and_b64 vcc, exec, s[4:5]
	s_waitcnt lgkmcnt(0)
	v_pk_mul_f32 v[8:9], v[6:7], v[8:9] op_sel_hi:[0,1]
	v_cvt_pk_bf16_f32 v8, v8, v9
	ds_read2_b32 v[10:11], v45 offset0:74 offset1:107
	s_waitcnt lgkmcnt(0)
	v_pk_mul_f32 v[10:11], v[6:7], v[10:11] op_sel_hi:[0,1]
	v_cvt_pk_bf16_f32 v9, v10, v11
	ds_read2_b32 v[10:11], v45 offset0:140 offset1:173
	s_waitcnt lgkmcnt(0)
	v_pk_mul_f32 v[10:11], v[6:7], v[10:11] op_sel_hi:[0,1]
	v_cvt_pk_bf16_f32 v10, v10, v11
	ds_read2_b32 v[12:13], v45 offset0:206 offset1:239
	s_waitcnt lgkmcnt(0)
	v_pk_mul_f32 v[12:13], v[6:7], v[12:13] op_sel_hi:[0,1]
	v_add_u32_e32 v7, s2, v7
	v_ashrrev_i32_e32 v6, 31, v7
	v_cvt_pk_bf16_f32 v11, v12, v13
	v_mul_lo_u32 v6, s12, v6
	v_mul_lo_u32 v14, s13, v7
	v_mad_u64_u32 v[12:13], s[20:21], s12, v7, 0
	v_add3_u32 v13, v13, v6, v14
	v_lshl_add_u64 v[12:13], v[12:13], 1, v[2:3]
	global_store_dwordx4 v[12:13], v[8:11], off
	v_mov_b32_e32 v6, 1.0
	s_nop 0
	v_mov_b32_e32 v8, 1.0
	s_cbranch_vccnz .LBB0_531
	global_load_dword v8, v[4:5], off offset:64
	s_waitcnt vmcnt(0)
.LBB0_531:
	ds_read2_b32 v[10:11], v45 offset0:16 offset1:49
	v_add_u32_e32 v7, s2, v7
	s_and_b64 vcc, exec, s[4:5]
	s_waitcnt lgkmcnt(0)
	v_pk_mul_f32 v[10:11], v[8:9], v[10:11] op_sel_hi:[0,1]
	v_cvt_pk_bf16_f32 v10, v10, v11
	ds_read2_b32 v[12:13], v45 offset0:82 offset1:115
	s_waitcnt lgkmcnt(0)
	v_pk_mul_f32 v[12:13], v[8:9], v[12:13] op_sel_hi:[0,1]
	v_cvt_pk_bf16_f32 v11, v12, v13
	ds_read2_b32 v[12:13], v45 offset0:148 offset1:181
	s_waitcnt lgkmcnt(0)
	v_pk_mul_f32 v[12:13], v[8:9], v[12:13] op_sel_hi:[0,1]
	v_cvt_pk_bf16_f32 v12, v12, v13
	ds_read2_b32 v[14:15], v45 offset0:214 offset1:247
	s_waitcnt lgkmcnt(0)
	v_pk_mul_f32 v[8:9], v[8:9], v[14:15] op_sel_hi:[0,1]
	v_cvt_pk_bf16_f32 v13, v8, v9
	v_ashrrev_i32_e32 v8, 31, v7
	v_mul_lo_u32 v14, s12, v8
	v_mul_lo_u32 v15, s13, v7
	v_mad_u64_u32 v[8:9], s[20:21], s12, v7, 0
	v_add3_u32 v9, v9, v14, v15
	v_lshl_add_u64 v[8:9], v[8:9], 1, v[2:3]
	global_store_dwordx4 v[8:9], v[10:13], off
	s_cbranch_vccnz .LBB0_487
	global_load_dword v6, v[4:5], off offset:96
	s_waitcnt vmcnt(0)
	s_branch .LBB0_487

; #define LAS __attribute__((address_space(3)))
; #define LDS_WAIT() asm volatile("s_waitcnt lgkmcnt(0)" ::: "memory")
; __device__ __forceinline__ unsigned cvt_pk_bf16(float lo, float hi) { const f32x2 v = {lo, hi}; unsigned r = __builtin_bit_cast(unsigned, __builtin_convertvector(v, bf16x2_t)); asm volatile("" : "+v"(r)); return r; }
; __device__ __forceinline__ void tr_item(const float* W, int ldn, int k0, int n0, const float* ks, const float* ns, bf16_t* WT, size_t dld, int rbase, int rstride, int dcol0, LAS float* scr, int lane) {
;     ...
;     for (int j = 0; j < 4; ++j) { const int n = (lane >> 3) + 8 * j; const LAS float* s = scr + (8 * c) * 33 + n; const float sc = ns ? ns[n] : 1.0f;
;         u32x4 o; o.x = cvt_pk_bf16(s[0 * 33] * sc, s[1 * 33] * sc); o.y = cvt_pk_bf16(s[2 * 33] * sc, s[3 * 33] * sc); o.z = cvt_pk_bf16(s[4 * 33] * sc, s[5 * 33] * sc); o.w = cvt_pk_bf16(s[6 * 33] * sc, s[7 * 33] * sc);
;         *(u32x4*)(WT + (size_t)(rbase + rstride * n) * dld + dcol0 + k0 + 8 * c) = o; }
;     LDS_WAIT(); asm volatile("" ::: "memory");
.LBB0_588:
	ds_read2_b32 v[4:5], v45 offset0:24 offset1:57
	s_addk_i32 s48, 0x400
	s_add_i32 s58, s58, 0x8000
	s_cmp_lt_i32 s48, s51
	s_waitcnt lgkmcnt(0)
	v_pk_mul_f32 v[4:5], v[6:7], v[4:5] op_sel_hi:[0,1]
	v_cvt_pk_bf16_f32 v8, v4, v5
	ds_read2_b32 v[4:5], v45 offset0:90 offset1:123
	s_waitcnt lgkmcnt(0)
	v_pk_mul_f32 v[4:5], v[6:7], v[4:5] op_sel_hi:[0,1]
	v_cvt_pk_bf16_f32 v9, v4, v5
	ds_read2_b32 v[4:5], v45 offset0:156 offset1:189
	s_waitcnt lgkmcnt(0)
	v_pk_mul_f32 v[4:5], v[6:7], v[4:5] op_sel_hi:[0,1]
	v_cvt_pk_bf16_f32 v10, v4, v5
	ds_read2_b32 v[4:5], v45 offset0:222 offset1:255
	s_waitcnt lgkmcnt(0)
	v_pk_mul_f32 v[4:5], v[6:7], v[4:5] op_sel_hi:[0,1]
	v_cvt_pk_bf16_f32 v11, v4, v5
	v_add_u32_e32 v4, s2, v7
	v_ashrrev_i32_e32 v5, 31, v4
	v_mul_lo_u32 v6, s12, v5
	v_mul_lo_u32 v7, s13, v4
	v_mad_u64_u32 v[4:5], s[2:3], s12, v4, 0
	v_add3_u32 v5, v5, v6, v7
	v_lshl_add_u64 v[2:3], v[4:5], 1, v[2:3]
	global_store_dwordx4 v[2:3], v[8:11], off
	s_waitcnt lgkmcnt(0)
	s_cbranch_scc0 .LBB0_549

; #define LAS __attribute__((address_space(3)))
; #define LDS_WAIT() asm volatile("s_waitcnt lgkmcnt(0)" ::: "memory")
; __device__ __forceinline__ unsigned cvt_pk_bf16(float lo, float hi) { const f32x2 v = {lo, hi}; unsigned r = __builtin_bit_cast(unsigned, __builtin_convertvector(v, bf16x2_t)); asm volatile("" : "+v"(r)); return r; }
; __device__ __forceinline__ void tr_item(const float* W, int ldn, int k0, int n0, const float* ks, const float* ns, bf16_t* WT, size_t dld, int rbase, int rstride, int dcol0, LAS float* scr, int lane) {
;     ...
;     const int c = lane & 7;
; #pragma unroll
;     for (int j = 0; j < 4; ++j) { const int n = (lane >> 3) + 8 * j; const LAS float* s = scr + (8 * c) * 33 + n; const float sc = ns ? ns[n] : 1.0f;
;         u32x4 o; o.x = cvt_pk_bf16(s[0 * 33] * sc, s[1 * 33] * sc); o.y = cvt_pk_bf16(s[2 * 33] * sc, s[3 * 33] * sc); o.z = cvt_pk_bf16(s[4 * 33] * sc, s[5 * 33] * sc); o.w = cvt_pk_bf16(s[6 * 33] * sc, s[7 * 33] * sc);
;         *(u32x4*)(WT + (size_t)(rbase + rstride * n) * dld + dcol0 + k0 + 8 * c) = o; }
;     LDS_WAIT(); asm volatile("" ::: "memory");
.LBB0_628:
	ds_read2_b32 v[10:11], v45 offset1:33
	s_lshl_b64 s[2:3], s[22:23], 1
	s_add_u32 s20, s8, s2
	s_addc_u32 s21, s9, s3
	s_lshl_b64 s[2:3], s[24:25], 1
	s_waitcnt lgkmcnt(0)
	v_pk_mul_f32 v[10:11], v[8:9], v[10:11] op_sel_hi:[0,1]
	v_cvt_pk_bf16_f32 v10, v10, v11
	ds_read2_b32 v[12:13], v45 offset0:66 offset1:99
	v_mul_lo_u32 v7, s59, v34
	s_add_u32 s2, s20, s2
	v_add_u32_e32 v7, v7, v37
	s_addc_u32 s3, s21, s3
	s_waitcnt lgkmcnt(0)
	v_pk_mul_f32 v[12:13], v[8:9], v[12:13] op_sel_hi:[0,1]
	v_cvt_pk_bf16_f32 v11, v12, v13
	ds_read2_b32 v[12:13], v45 offset0:132 offset1:165
	v_lshl_add_u64 v[2:3], s[2:3], 0, v[0:1]
	s_and_b64 vcc, exec, s[4:5]
	s_waitcnt lgkmcnt(0)
	v_pk_mul_f32 v[12:13], v[8:9], v[12:13] op_sel_hi:[0,1]
	v_cvt_pk_bf16_f32 v12, v12, v13
	ds_read2_b32 v[14:15], v45 offset0:198 offset1:231
	s_waitcnt lgkmcnt(0)
	v_pk_mul_f32 v[8:9], v[8:9], v[14:15] op_sel_hi:[0,1]
	v_cvt_pk_bf16_f32 v13, v8, v9
	v_ashrrev_i32_e32 v8, 31, v7
	v_mul_lo_u32 v14, s12, v8
	v_mul_lo_u32 v15, s13, v7
	v_mad_u64_u32 v[8:9], s[2:3], s12, v7, 0
	v_add3_u32 v9, v9, v14, v15
	v_lshl_add_u64 v[8:9], v[8:9], 1, v[2:3]
	global_store_dwordx4 v[8:9], v[10:13], off
	s_cbranch_vccnz .LBB0_630
	global_load_dword v6, v[4:5], off offset:32
	s_waitcnt vmcnt(0)
.LBB0_630:
	ds_read2_b32 v[8:9], v45 offset0:8 offset1:41
	s_lshl_b32 s2, s59, 3
	s_and_b64 vcc, exec, s[4:5]
	s_waitcnt lgkmcnt(0)
	v_pk_mul_f32 v[8:9], v[6:7], v[8:9] op_sel_hi:[0,1]
	v_cvt_pk_bf16_f32 v8, v8, v9
	ds_read2_b32 v[10:11], v45 offset0:74 offset1:107
	s_waitcnt lgkmcnt(0)
	v_pk_mul_f32 v[10:11], v[6:7], v[10:11] op_sel_hi:[0,1]
	v_cvt_pk_bf16_f32 v9, v10, v11
	ds_read2_b32 v[10:11], v45 offset0:140 offset1:173
	s_waitcnt lgkmcnt(0)
	v_pk_mul_f32 v[10:11], v[6:7], v[10:11] op_sel_hi:[0,1]
	v_cvt_pk_bf16_f32 v10, v10, v11
	ds_read2_b32 v[12:13], v45 offset0:206 offset1:239
	s_waitcnt lgkmcnt(0)
	v_pk_mul_f32 v[12:13], v[6:7], v[12:13] op_sel_hi:[0,1]
	v_add_u32_e32 v7, s2, v7
	v_ashrrev_i32_e32 v6, 31, v7
	v_cvt_pk_bf16_f32 v11, v12, v13
	v_mul_lo_u32 v6, s12, v6
	v_mul_lo_u32 v14, s13, v7
	v_mad_u64_u32 v[12:13], s[20:21], s12, v7, 0
	v_add3_u32 v13, v13, v6, v14
	v_lshl_add_u64 v[12:13], v[12:13], 1, v[2:3]
	global_store_dwordx4 v[12:13], v[8:11], off
	v_mov_b32_e32 v6, 1.0
	s_nop 0
	v_mov_b32_e32 v8, 1.0
	s_cbranch_vccnz .LBB0_632
	global_load_dword v8, v[4:5], off offset:64
	s_waitcnt vmcnt(0)

; #define LAS __attribute__((address_space(3)))
; #define LDS_WAIT() asm volatile("s_waitcnt lgkmcnt(0)" ::: "memory")
; __device__ __forceinline__ unsigned cvt_pk_bf16(float lo, float hi) { const f32x2 v = {lo, hi}; unsigned r = __builtin_bit_cast(unsigned, __builtin_convertvector(v, bf16x2_t)); asm volatile("" : "+v"(r)); return r; }
; __device__ __forceinline__ void tr_item(const float* W, int ldn, int k0, int n0, const float* ks, const float* ns, bf16_t* WT, size_t dld, int rbase, int rstride, int dcol0, LAS float* scr, int lane) {
;     ...
;     for (int j = 0; j < 4; ++j) { const int n = (lane >> 3) + 8 * j; const LAS float* s = scr + (8 * c) * 33 + n; const float sc = ns ? ns[n] : 1.0f;
;         u32x4 o; o.x = cvt_pk_bf16(s[0 * 33] * sc, s[1 * 33] * sc); o.y = cvt_pk_bf16(s[2 * 33] * sc, s[3 * 33] * sc); o.z = cvt_pk_bf16(s[4 * 33] * sc, s[5 * 33] * sc); o.w = cvt_pk_bf16(s[6 * 33] * sc, s[7 * 33] * sc);
;         *(u32x4*)(WT + (size_t)(rbase + rstride * n) * dld + dcol0 + k0 + 8 * c) = o; }
;     LDS_WAIT(); asm volatile("" ::: "memory");
.LBB0_915:
	ds_read2_b32 v[4:5], v41 offset0:24 offset1:57
	s_add_i32 s27, s27, s28
	s_add_i32 s59, s59, s60
	s_cmp_lt_i32 s27, s52
	s_waitcnt lgkmcnt(0)
	v_pk_mul_f32 v[4:5], v[6:7], v[4:5] op_sel_hi:[0,1]
	v_cvt_pk_bf16_f32 v8, v4, v5
	ds_read2_b32 v[4:5], v41 offset0:90 offset1:123
	s_waitcnt lgkmcnt(0)
	v_pk_mul_f32 v[4:5], v[6:7], v[4:5] op_sel_hi:[0,1]
	v_cvt_pk_bf16_f32 v9, v4, v5
	ds_read2_b32 v[4:5], v41 offset0:156 offset1:189
	s_waitcnt lgkmcnt(0)
	v_pk_mul_f32 v[4:5], v[6:7], v[4:5] op_sel_hi:[0,1]
	v_cvt_pk_bf16_f32 v10, v4, v5
	ds_read2_b32 v[4:5], v41 offset0:222 offset1:255
	s_waitcnt lgkmcnt(0)
	v_pk_mul_f32 v[4:5], v[6:7], v[4:5] op_sel_hi:[0,1]
	v_cvt_pk_bf16_f32 v11, v4, v5
	v_add_u32_e32 v4, s2, v7
	v_ashrrev_i32_e32 v5, 31, v4
	v_mul_lo_u32 v6, s12, v5
	v_mul_lo_u32 v7, s13, v4
	v_mad_u64_u32 v[4:5], s[2:3], s12, v4, 0
	v_add3_u32 v5, v5, v6, v7
	v_lshl_add_u64 v[2:3], v[4:5], 1, v[2:3]
	global_store_dwordx4 v[2:3], v[8:11], off
	s_waitcnt lgkmcnt(0)
	s_cbranch_scc0 .LBB0_876

; #define LAS __attribute__((address_space(3)))
; #define LDS_WAIT() asm volatile("s_waitcnt lgkmcnt(0)" ::: "memory")
; __device__ __forceinline__ unsigned cvt_pk_bf16(float lo, float hi) { const f32x2 v = {lo, hi}; unsigned r = __builtin_bit_cast(unsigned, __builtin_convertvector(v, bf16x2_t)); asm volatile("" : "+v"(r)); return r; }
; __device__ __forceinline__ void tr_item(const float* W, int ldn, int k0, int n0, const float* ks, const float* ns, bf16_t* WT, size_t dld, int rbase, int rstride, int dcol0, LAS float* scr, int lane) {
;     ...
;     for (int i = 0; i < 8; ++i) { const int kk = 8 * i + (lane >> 3); const float s = ks ? ks[k0 + kk] : 1.0f; LAS float* d = scr + kk * 33 + 4 * (lane & 7);
;         d[0] = v[i][0] * s; d[1] = v[i][1] * s; d[2] = v[i][2] * s; d[3] = v[i][3] * s; }
;     LDS_WAIT(); asm volatile("" ::: "memory");
;     const int c = lane & 7;
; #pragma unroll
;     for (int j = 0; j < 4; ++j) { const int n = (lane >> 3) + 8 * j; const LAS float* s = scr + (8 * c) * 33 + n; const float sc = ns ? ns[n] : 1.0f;
;         u32x4 o; o.x = cvt_pk_bf16(s[0 * 33] * sc, s[1 * 33] * sc); o.y = cvt_pk_bf16(s[2 * 33] * sc, s[3 * 33] * sc); o.z = cvt_pk_bf16(s[4 * 33] * sc, s[5 * 33] * sc); o.w = cvt_pk_bf16(s[6 * 33] * sc, s[7 * 33] * sc);
;         *(u32x4*)(WT + (size_t)(rbase + rstride * n) * dld + dcol0 + k0 + 8 * c) = o; }
;     LDS_WAIT(); asm volatile("" ::: "memory");
.LBB0_953:
	v_add_u32_e32 v11, 0x18c0, v45
	ds_write2_b32 v11, v6, v7 offset1:1
	v_add_u32_e32 v6, 0x18c8, v45
	ds_write2_b32 v6, v8, v9 offset1:1
	s_waitcnt vmcnt(0)
	v_pk_mul_f32 v[2:3], v[2:3], v[10:11] op_sel_hi:[1,0]
	v_add_u32_e32 v6, 0x1ce0, v45
	ds_write2_b32 v6, v2, v3 offset1:1
	v_pk_mul_f32 v[2:3], v[4:5], v[10:11] op_sel_hi:[1,0]
	v_add_u32_e32 v4, 0x1ce8, v45
	ds_write2_b32 v4, v2, v3 offset1:1
	s_lshl_b64 s[2:3], s[20:21], 2
	s_waitcnt lgkmcnt(0)
	s_add_u32 s2, s14, s2
	s_addc_u32 s3, s15, s3
	v_cndmask_b32_e64 v2, 0, 1, s[18:19]
	v_mov_b32_e32 v6, 1.0
	v_cmp_ne_u32_e64 s[4:5], 1, v2
	s_andn2_b64 vcc, exec, s[18:19]
	v_lshl_add_u64 v[4:5], v[34:35], 2, s[2:3]
	v_mov_b32_e32 v8, 1.0
	s_cbranch_vccnz .LBB0_955
	global_load_dword v8, v[4:5], off
	s_waitcnt vmcnt(0)
.LBB0_955:
	ds_read2_b32 v[10:11], v41 offset1:33
	s_lshl_b64 s[2:3], s[22:23], 1
	s_add_u32 s20, s8, s2
	s_addc_u32 s21, s9, s3
	s_lshl_b64 s[2:3], s[24:25], 1
	s_waitcnt lgkmcnt(0)
	v_pk_mul_f32 v[10:11], v[8:9], v[10:11] op_sel_hi:[0,1]
	v_cvt_pk_bf16_f32 v10, v10, v11
	ds_read2_b32 v[12:13], v41 offset0:66 offset1:99
	v_mul_lo_u32 v7, s62, v34
	s_add_u32 s2, s20, s2
	v_add_u32_e32 v7, v7, v37
	s_addc_u32 s3, s21, s3
	s_waitcnt lgkmcnt(0)
	v_pk_mul_f32 v[12:13], v[8:9], v[12:13] op_sel_hi:[0,1]
	v_cvt_pk_bf16_f32 v11, v12, v13
	ds_read2_b32 v[12:13], v41 offset0:132 offset1:165
	v_lshl_add_u64 v[2:3], s[2:3], 0, v[0:1]
	s_and_b64 vcc, exec, s[4:5]
	s_waitcnt lgkmcnt(0)
	v_pk_mul_f32 v[12:13], v[8:9], v[12:13] op_sel_hi:[0,1]
	v_cvt_pk_bf16_f32 v12, v12, v13
	ds_read2_b32 v[14:15], v41 offset0:198 offset1:231
	s_waitcnt lgkmcnt(0)
	v_pk_mul_f32 v[8:9], v[8:9], v[14:15] op_sel_hi:[0,1]
	v_cvt_pk_bf16_f32 v13, v8, v9
	v_ashrrev_i32_e32 v8, 31, v7
	v_mul_lo_u32 v14, s12, v8
	v_mul_lo_u32 v15, s13, v7
	v_mad_u64_u32 v[8:9], s[2:3], s12, v7, 0
	v_add3_u32 v9, v9, v14, v15
	v_lshl_add_u64 v[8:9], v[8:9], 1, v[2:3]
	global_store_dwordx4 v[8:9], v[10:13], off
	s_cbranch_vccnz .LBB0_957
	global_load_dword v6, v[4:5], off offset:32
	s_waitcnt vmcnt(0)
.LBB0_957:
	ds_read2_b32 v[8:9], v41 offset0:8 offset1:41
	s_lshl_b32 s2, s62, 3
	s_and_b64 vcc, exec, s[4:5]
	s_waitcnt lgkmcnt(0)
	v_pk_mul_f32 v[8:9], v[6:7], v[8:9] op_sel_hi:[0,1]
	v_cvt_pk_bf16_f32 v8, v8, v9
	ds_read2_b32 v[10:11], v41 offset0:74 offset1:107
	s_waitcnt lgkmcnt(0)
	v_pk_mul_f32 v[10:11], v[6:7], v[10:11] op_sel_hi:[0,1]
	v_cvt_pk_bf16_f32 v9, v10, v11
	ds_read2_b32 v[10:11], v41 offset0:140 offset1:173
	s_waitcnt lgkmcnt(0)
	v_pk_mul_f32 v[10:11], v[6:7], v[10:11] op_sel_hi:[0,1]
	v_cvt_pk_bf16_f32 v10, v10, v11
	ds_read2_b32 v[12:13], v41 offset0:206 offset1:239
	s_waitcnt lgkmcnt(0)
	v_pk_mul_f32 v[12:13], v[6:7], v[12:13] op_sel_hi:[0,1]
	v_add_u32_e32 v7, s2, v7
	v_ashrrev_i32_e32 v6, 31, v7
	v_cvt_pk_bf16_f32 v11, v12, v13
	v_mul_lo_u32 v6, s12, v6
	v_mul_lo_u32 v14, s13, v7
	v_mad_u64_u32 v[12:13], s[20:21], s12, v7, 0
	v_add3_u32 v13, v13, v6, v14
	v_lshl_add_u64 v[12:13], v[12:13], 1, v[2:3]
	global_store_dwordx4 v[12:13], v[8:11], off
	v_mov_b32_e32 v6, 1.0
	s_nop 0
	v_mov_b32_e32 v8, 1.0
	s_cbranch_vccnz .LBB0_959
	global_load_dword v8, v[4:5], off offset:64
	s_waitcnt vmcnt(0)
.LBB0_959:
	ds_read2_b32 v[10:11], v41 offset0:16 offset1:49
	v_add_u32_e32 v7, s2, v7
	s_and_b64 vcc, exec, s[4:5]
	s_waitcnt lgkmcnt(0)
	v_pk_mul_f32 v[10:11], v[8:9], v[10:11] op_sel_hi:[0,1]
	v_cvt_pk_bf16_f32 v10, v10, v11
	ds_read2_b32 v[12:13], v41 offset0:82 offset1:115
	s_waitcnt lgkmcnt(0)
	v_pk_mul_f32 v[12:13], v[8:9], v[12:13] op_sel_hi:[0,1]
	v_cvt_pk_bf16_f32 v11, v12, v13
	ds_read2_b32 v[12:13], v41 offset0:148 offset1:181
	s_waitcnt lgkmcnt(0)
	v_pk_mul_f32 v[12:13], v[8:9], v[12:13] op_sel_hi:[0,1]
	v_cvt_pk_bf16_f32 v12, v12, v13
	ds_read2_b32 v[14:15], v41 offset0:214 offset1:247
	s_waitcnt lgkmcnt(0)
	v_pk_mul_f32 v[8:9], v[8:9], v[14:15] op_sel_hi:[0,1]
	v_cvt_pk_bf16_f32 v13, v8, v9
	v_ashrrev_i32_e32 v8, 31, v7
	v_mul_lo_u32 v14, s12, v8
	v_mul_lo_u32 v15, s13, v7
	v_mad_u64_u32 v[8:9], s[20:21], s12, v7, 0
	v_add3_u32 v9, v9, v14, v15
	v_lshl_add_u64 v[8:9], v[8:9], 1, v[2:3]
	global_store_dwordx4 v[8:9], v[10:13], off
	s_cbranch_vccnz .LBB0_915
	global_load_dword v6, v[4:5], off offset:96
	s_waitcnt vmcnt(0)
	s_branch .LBB0_915

; #define LAS __attribute__((address_space(3)))
; #define LDS_WAIT() asm volatile("s_waitcnt lgkmcnt(0)" ::: "memory")
; __device__ __forceinline__ unsigned cvt_pk_bf16(float lo, float hi) { const f32x2 v = {lo, hi}; unsigned r = __builtin_bit_cast(unsigned, __builtin_convertvector(v, bf16x2_t)); asm volatile("" : "+v"(r)); return r; }
; __device__ __forceinline__ void tr_item(const float* W, int ldn, int k0, int n0, const float* ks, const float* ns, bf16_t* WT, size_t dld, int rbase, int rstride, int dcol0, LAS float* scr, int lane) {
;     ...
;     for (int j = 0; j < 4; ++j) { const int n = (lane >> 3) + 8 * j; const LAS float* s = scr + (8 * c) * 33 + n; const float sc = ns ? ns[n] : 1.0f;
;         u32x4 o; o.x = cvt_pk_bf16(s[0 * 33] * sc, s[1 * 33] * sc); o.y = cvt_pk_bf16(s[2 * 33] * sc, s[3 * 33] * sc); o.z = cvt_pk_bf16(s[4 * 33] * sc, s[5 * 33] * sc); o.w = cvt_pk_bf16(s[6 * 33] * sc, s[7 * 33] * sc);
;         *(u32x4*)(WT + (size_t)(rbase + rstride * n) * dld + dcol0 + k0 + 8 * c) = o; }
;     LDS_WAIT(); asm volatile("" ::: "memory");
.LBB0_1006:
	ds_read2_b32 v[4:5], v41 offset0:24 offset1:57
	s_addk_i32 s27, 0x3c0
	s_addk_i32 s58, 0x7800
	s_cmp_lt_i32 s27, s51
	s_waitcnt lgkmcnt(0)
	v_pk_mul_f32 v[4:5], v[6:7], v[4:5] op_sel_hi:[0,1]
	v_cvt_pk_bf16_f32 v8, v4, v5
	ds_read2_b32 v[4:5], v41 offset0:90 offset1:123
	s_waitcnt lgkmcnt(0)
	v_pk_mul_f32 v[4:5], v[6:7], v[4:5] op_sel_hi:[0,1]
	v_cvt_pk_bf16_f32 v9, v4, v5
	ds_read2_b32 v[4:5], v41 offset0:156 offset1:189
	s_waitcnt lgkmcnt(0)
	v_pk_mul_f32 v[4:5], v[6:7], v[4:5] op_sel_hi:[0,1]
	v_cvt_pk_bf16_f32 v10, v4, v5
	ds_read2_b32 v[4:5], v41 offset0:222 offset1:255
	s_waitcnt lgkmcnt(0)
	v_pk_mul_f32 v[4:5], v[6:7], v[4:5] op_sel_hi:[0,1]
	v_cvt_pk_bf16_f32 v11, v4, v5
	v_add_u32_e32 v4, s2, v7
	v_ashrrev_i32_e32 v5, 31, v4
	v_mul_lo_u32 v6, s12, v5
	v_mul_lo_u32 v7, s13, v4
	v_mad_u64_u32 v[4:5], s[2:3], s12, v4, 0
	v_add3_u32 v5, v5, v6, v7
	v_lshl_add_u64 v[2:3], v[4:5], 1, v[2:3]
	global_store_dwordx4 v[2:3], v[8:11], off
	s_waitcnt lgkmcnt(0)
	s_cbranch_scc0 .LBB0_967

; #define LAS __attribute__((address_space(3)))
; #define LDS_WAIT() asm volatile("s_waitcnt lgkmcnt(0)" ::: "memory")
; __device__ __forceinline__ unsigned cvt_pk_bf16(float lo, float hi) { const f32x2 v = {lo, hi}; unsigned r = __builtin_bit_cast(unsigned, __builtin_convertvector(v, bf16x2_t)); asm volatile("" : "+v"(r)); return r; }
; __device__ __forceinline__ void tr_item(const float* W, int ldn, int k0, int n0, const float* ks, const float* ns, bf16_t* WT, size_t dld, int rbase, int rstride, int dcol0, LAS float* scr, int lane) {
;     ...
;     const int c = lane & 7;
; #pragma unroll
;     for (int j = 0; j < 4; ++j) { const int n = (lane >> 3) + 8 * j; const LAS float* s = scr + (8 * c) * 33 + n; const float sc = ns ? ns[n] : 1.0f;
;         u32x4 o; o.x = cvt_pk_bf16(s[0 * 33] * sc, s[1 * 33] * sc); o.y = cvt_pk_bf16(s[2 * 33] * sc, s[3 * 33] * sc); o.z = cvt_pk_bf16(s[4 * 33] * sc, s[5 * 33] * sc); o.w = cvt_pk_bf16(s[6 * 33] * sc, s[7 * 33] * sc);
;         *(u32x4*)(WT + (size_t)(rbase + rstride * n) * dld + dcol0 + k0 + 8 * c) = o; }
;     LDS_WAIT(); asm volatile("" ::: "memory");
.LBB0_1046:
	ds_read2_b32 v[10:11], v41 offset1:33
	s_lshl_b64 s[2:3], s[22:23], 1
	s_add_u32 s20, s8, s2
	s_addc_u32 s21, s9, s3
	s_lshl_b64 s[2:3], s[24:25], 1
	s_waitcnt lgkmcnt(0)
	v_pk_mul_f32 v[10:11], v[8:9], v[10:11] op_sel_hi:[0,1]
	v_cvt_pk_bf16_f32 v10, v10, v11
	ds_read2_b32 v[12:13], v41 offset0:66 offset1:99
	v_mul_lo_u32 v7, s59, v34
	s_add_u32 s2, s20, s2
	v_add_u32_e32 v7, v7, v37
	s_addc_u32 s3, s21, s3
	s_waitcnt lgkmcnt(0)
	v_pk_mul_f32 v[12:13], v[8:9], v[12:13] op_sel_hi:[0,1]
	v_cvt_pk_bf16_f32 v11, v12, v13
	ds_read2_b32 v[12:13], v41 offset0:132 offset1:165
	v_lshl_add_u64 v[2:3], s[2:3], 0, v[0:1]
	s_and_b64 vcc, exec, s[4:5]
	s_waitcnt lgkmcnt(0)
	v_pk_mul_f32 v[12:13], v[8:9], v[12:13] op_sel_hi:[0,1]
	v_cvt_pk_bf16_f32 v12, v12, v13
	ds_read2_b32 v[14:15], v41 offset0:198 offset1:231
	s_waitcnt lgkmcnt(0)
	v_pk_mul_f32 v[8:9], v[8:9], v[14:15] op_sel_hi:[0,1]
	v_cvt_pk_bf16_f32 v13, v8, v9
	v_ashrrev_i32_e32 v8, 31, v7
	v_mul_lo_u32 v14, s12, v8
	v_mul_lo_u32 v15, s13, v7
	v_mad_u64_u32 v[8:9], s[2:3], s12, v7, 0
	v_add3_u32 v9, v9, v14, v15
	v_lshl_add_u64 v[8:9], v[8:9], 1, v[2:3]
	global_store_dwordx4 v[8:9], v[10:13], off
	s_cbranch_vccnz .LBB0_1048
	global_load_dword v6, v[4:5], off offset:32
	s_waitcnt vmcnt(0)
.LBB0_1048:
	ds_read2_b32 v[8:9], v41 offset0:8 offset1:41
	s_lshl_b32 s2, s59, 3
	s_and_b64 vcc, exec, s[4:5]
	s_waitcnt lgkmcnt(0)
	v_pk_mul_f32 v[8:9], v[6:7], v[8:9] op_sel_hi:[0,1]
	v_cvt_pk_bf16_f32 v8, v8, v9
	ds_read2_b32 v[10:11], v41 offset0:74 offset1:107
	s_waitcnt lgkmcnt(0)
	v_pk_mul_f32 v[10:11], v[6:7], v[10:11] op_sel_hi:[0,1]
	v_cvt_pk_bf16_f32 v9, v10, v11
	ds_read2_b32 v[10:11], v41 offset0:140 offset1:173
	s_waitcnt lgkmcnt(0)
	v_pk_mul_f32 v[10:11], v[6:7], v[10:11] op_sel_hi:[0,1]
	v_cvt_pk_bf16_f32 v10, v10, v11
	ds_read2_b32 v[12:13], v41 offset0:206 offset1:239
	s_waitcnt lgkmcnt(0)
	v_pk_mul_f32 v[12:13], v[6:7], v[12:13] op_sel_hi:[0,1]
	v_add_u32_e32 v7, s2, v7
	v_ashrrev_i32_e32 v6, 31, v7
	v_cvt_pk_bf16_f32 v11, v12, v13
	v_mul_lo_u32 v6, s12, v6
	v_mul_lo_u32 v14, s13, v7
	v_mad_u64_u32 v[12:13], s[20:21], s12, v7, 0
	v_add3_u32 v13, v13, v6, v14
	v_lshl_add_u64 v[12:13], v[12:13], 1, v[2:3]
	global_store_dwordx4 v[12:13], v[8:11], off
	v_mov_b32_e32 v6, 1.0
	s_nop 0
	v_mov_b32_e32 v8, 1.0
	s_cbranch_vccnz .LBB0_1050
	global_load_dword v8, v[4:5], off offset:64
	s_waitcnt vmcnt(0)

; #define LAS __attribute__((address_space(3)))
; #define LDS_WAIT() asm volatile("s_waitcnt lgkmcnt(0)" ::: "memory")
; __device__ __forceinline__ unsigned cvt_pk_bf16(float lo, float hi) { const f32x2 v = {lo, hi}; unsigned r = __builtin_bit_cast(unsigned, __builtin_convertvector(v, bf16x2_t)); asm volatile("" : "+v"(r)); return r; }
; __device__ __forceinline__ void tr_item(const float* W, int ldn, int k0, int n0, const float* ks, const float* ns, bf16_t* WT, size_t dld, int rbase, int rstride, int dcol0, LAS float* scr, int lane) {
;     ...
;     for (int j = 0; j < 4; ++j) { const int n = (lane >> 3) + 8 * j; const LAS float* s = scr + (8 * c) * 33 + n; const float sc = ns ? ns[n] : 1.0f;
;         u32x4 o; o.x = cvt_pk_bf16(s[0 * 33] * sc, s[1 * 33] * sc); o.y = cvt_pk_bf16(s[2 * 33] * sc, s[3 * 33] * sc); o.z = cvt_pk_bf16(s[4 * 33] * sc, s[5 * 33] * sc); o.w = cvt_pk_bf16(s[6 * 33] * sc, s[7 * 33] * sc);
;         *(u32x4*)(WT + (size_t)(rbase + rstride * n) * dld + dcol0 + k0 + 8 * c) = o; }
;     LDS_WAIT(); asm volatile("" ::: "memory");
.LBB0_1910:
	ds_read2_b32 v[4:5], v41 offset0:24 offset1:57
	s_add_i32 s4, s4, s5
	s_add_i32 s59, s59, s60
	s_cmp_lt_i32 s4, s52
	s_waitcnt lgkmcnt(0)
	v_pk_mul_f32 v[4:5], v[6:7], v[4:5] op_sel_hi:[0,1]
	v_cvt_pk_bf16_f32 v8, v4, v5
	ds_read2_b32 v[4:5], v41 offset0:90 offset1:123
	s_waitcnt lgkmcnt(0)
	v_pk_mul_f32 v[4:5], v[6:7], v[4:5] op_sel_hi:[0,1]
	v_cvt_pk_bf16_f32 v9, v4, v5
	ds_read2_b32 v[4:5], v41 offset0:156 offset1:189
	s_waitcnt lgkmcnt(0)
	v_pk_mul_f32 v[4:5], v[6:7], v[4:5] op_sel_hi:[0,1]
	v_cvt_pk_bf16_f32 v10, v4, v5
	ds_read2_b32 v[4:5], v41 offset0:222 offset1:255
	s_waitcnt lgkmcnt(0)
	v_pk_mul_f32 v[4:5], v[6:7], v[4:5] op_sel_hi:[0,1]
	v_cvt_pk_bf16_f32 v11, v4, v5
	v_add_u32_e32 v4, s2, v7
	v_ashrrev_i32_e32 v5, 31, v4
	v_mul_lo_u32 v6, s14, v5
	v_mul_lo_u32 v7, s15, v4
	v_mad_u64_u32 v[4:5], s[2:3], s14, v4, 0
	v_add3_u32 v5, v5, v6, v7
	v_lshl_add_u64 v[2:3], v[4:5], 1, v[2:3]
	global_store_dwordx4 v[2:3], v[8:11], off
	s_waitcnt lgkmcnt(0)
	s_cbranch_scc0 .LBB0_1871

; #define LAS __attribute__((address_space(3)))
; #define LDS_WAIT() asm volatile("s_waitcnt lgkmcnt(0)" ::: "memory")
; __device__ __forceinline__ unsigned cvt_pk_bf16(float lo, float hi) { const f32x2 v = {lo, hi}; unsigned r = __builtin_bit_cast(unsigned, __builtin_convertvector(v, bf16x2_t)); asm volatile("" : "+v"(r)); return r; }
; __device__ __forceinline__ void tr_item(const float* W, int ldn, int k0, int n0, const float* ks, const float* ns, bf16_t* WT, size_t dld, int rbase, int rstride, int dcol0, LAS float* scr, int lane) {
;     ...
;     for (int i = 0; i < 8; ++i) { const int kk = 8 * i + (lane >> 3); const float s = ks ? ks[k0 + kk] : 1.0f; LAS float* d = scr + kk * 33 + 4 * (lane & 7);
;         d[0] = v[i][0] * s; d[1] = v[i][1] * s; d[2] = v[i][2] * s; d[3] = v[i][3] * s; }
;     LDS_WAIT(); asm volatile("" ::: "memory");
;     const int c = lane & 7;
; #pragma unroll
;     for (int j = 0; j < 4; ++j) { const int n = (lane >> 3) + 8 * j; const LAS float* s = scr + (8 * c) * 33 + n; const float sc = ns ? ns[n] : 1.0f;
;         u32x4 o; o.x = cvt_pk_bf16(s[0 * 33] * sc, s[1 * 33] * sc); o.y = cvt_pk_bf16(s[2 * 33] * sc, s[3 * 33] * sc); o.z = cvt_pk_bf16(s[4 * 33] * sc, s[5 * 33] * sc); o.w = cvt_pk_bf16(s[6 * 33] * sc, s[7 * 33] * sc);
;         *(u32x4*)(WT + (size_t)(rbase + rstride * n) * dld + dcol0 + k0 + 8 * c) = o; }
;     LDS_WAIT(); asm volatile("" ::: "memory");
.LBB0_1948:
	v_add_u32_e32 v11, 0x18c0, v45
	ds_write2_b32 v11, v6, v7 offset1:1
	v_add_u32_e32 v6, 0x18c8, v45
	ds_write2_b32 v6, v8, v9 offset1:1
	s_waitcnt vmcnt(0)
	v_pk_mul_f32 v[2:3], v[2:3], v[10:11] op_sel_hi:[1,0]
	v_add_u32_e32 v6, 0x1ce0, v45
	ds_write2_b32 v6, v2, v3 offset1:1
	v_pk_mul_f32 v[2:3], v[4:5], v[10:11] op_sel_hi:[1,0]
	v_add_u32_e32 v4, 0x1ce8, v45
	ds_write2_b32 v4, v2, v3 offset1:1
	s_lshl_b64 s[2:3], s[22:23], 2
	s_waitcnt lgkmcnt(0)
	s_add_u32 s2, s16, s2
	s_addc_u32 s3, s17, s3
	v_cndmask_b32_e64 v2, 0, 1, s[20:21]
	v_mov_b32_e32 v6, 1.0
	v_cmp_ne_u32_e64 s[6:7], 1, v2
	s_andn2_b64 vcc, exec, s[20:21]
	v_lshl_add_u64 v[4:5], v[34:35], 2, s[2:3]
	v_mov_b32_e32 v8, 1.0
	s_cbranch_vccnz .LBB0_1950
	global_load_dword v8, v[4:5], off
	s_waitcnt vmcnt(0)
.LBB0_1950:
	ds_read2_b32 v[10:11], v41 offset1:33
	s_lshl_b64 s[2:3], s[24:25], 1
	s_add_u32 s22, s10, s2
	s_addc_u32 s23, s11, s3
	s_lshl_b64 s[2:3], s[26:27], 1
	s_waitcnt lgkmcnt(0)
	v_pk_mul_f32 v[10:11], v[8:9], v[10:11] op_sel_hi:[0,1]
	v_cvt_pk_bf16_f32 v10, v10, v11
	ds_read2_b32 v[12:13], v41 offset0:66 offset1:99
	v_mul_lo_u32 v7, s62, v34
	s_add_u32 s2, s22, s2
	v_add_u32_e32 v7, v7, v37
	s_addc_u32 s3, s23, s3
	s_waitcnt lgkmcnt(0)
	v_pk_mul_f32 v[12:13], v[8:9], v[12:13] op_sel_hi:[0,1]
	v_cvt_pk_bf16_f32 v11, v12, v13
	ds_read2_b32 v[12:13], v41 offset0:132 offset1:165
	v_lshl_add_u64 v[2:3], s[2:3], 0, v[0:1]
	s_and_b64 vcc, exec, s[6:7]
	s_waitcnt lgkmcnt(0)
	v_pk_mul_f32 v[12:13], v[8:9], v[12:13] op_sel_hi:[0,1]
	v_cvt_pk_bf16_f32 v12, v12, v13
	ds_read2_b32 v[14:15], v41 offset0:198 offset1:231
	s_waitcnt lgkmcnt(0)
	v_pk_mul_f32 v[8:9], v[8:9], v[14:15] op_sel_hi:[0,1]
	v_cvt_pk_bf16_f32 v13, v8, v9
	v_ashrrev_i32_e32 v8, 31, v7
	v_mul_lo_u32 v14, s14, v8
	v_mul_lo_u32 v15, s15, v7
	v_mad_u64_u32 v[8:9], s[2:3], s14, v7, 0
	v_add3_u32 v9, v9, v14, v15
	v_lshl_add_u64 v[8:9], v[8:9], 1, v[2:3]
	global_store_dwordx4 v[8:9], v[10:13], off
	s_cbranch_vccnz .LBB0_1952
	global_load_dword v6, v[4:5], off offset:32
	s_waitcnt vmcnt(0)
.LBB0_1952:
	ds_read2_b32 v[8:9], v41 offset0:8 offset1:41
	s_lshl_b32 s2, s62, 3
	s_and_b64 vcc, exec, s[6:7]
	s_waitcnt lgkmcnt(0)
	v_pk_mul_f32 v[8:9], v[6:7], v[8:9] op_sel_hi:[0,1]
	v_cvt_pk_bf16_f32 v8, v8, v9
	ds_read2_b32 v[10:11], v41 offset0:74 offset1:107
	s_waitcnt lgkmcnt(0)
	v_pk_mul_f32 v[10:11], v[6:7], v[10:11] op_sel_hi:[0,1]
	v_cvt_pk_bf16_f32 v9, v10, v11
	ds_read2_b32 v[10:11], v41 offset0:140 offset1:173
	s_waitcnt lgkmcnt(0)
	v_pk_mul_f32 v[10:11], v[6:7], v[10:11] op_sel_hi:[0,1]
	v_cvt_pk_bf16_f32 v10, v10, v11
	ds_read2_b32 v[12:13], v41 offset0:206 offset1:239
	s_waitcnt lgkmcnt(0)
	v_pk_mul_f32 v[12:13], v[6:7], v[12:13] op_sel_hi:[0,1]
	v_add_u32_e32 v7, s2, v7
	v_ashrrev_i32_e32 v6, 31, v7
	v_cvt_pk_bf16_f32 v11, v12, v13
	v_mul_lo_u32 v6, s14, v6
	v_mul_lo_u32 v14, s15, v7
	v_mad_u64_u32 v[12:13], s[22:23], s14, v7, 0
	v_add3_u32 v13, v13, v6, v14
	v_lshl_add_u64 v[12:13], v[12:13], 1, v[2:3]
	global_store_dwordx4 v[12:13], v[8:11], off
	v_mov_b32_e32 v6, 1.0
	s_nop 0
	v_mov_b32_e32 v8, 1.0
	s_cbranch_vccnz .LBB0_1954
	global_load_dword v8, v[4:5], off offset:64
	s_waitcnt vmcnt(0)
.LBB0_1954:
	ds_read2_b32 v[10:11], v41 offset0:16 offset1:49
	v_add_u32_e32 v7, s2, v7
	s_and_b64 vcc, exec, s[6:7]
	s_waitcnt lgkmcnt(0)
	v_pk_mul_f32 v[10:11], v[8:9], v[10:11] op_sel_hi:[0,1]
	v_cvt_pk_bf16_f32 v10, v10, v11
	ds_read2_b32 v[12:13], v41 offset0:82 offset1:115
	s_waitcnt lgkmcnt(0)
	v_pk_mul_f32 v[12:13], v[8:9], v[12:13] op_sel_hi:[0,1]
	v_cvt_pk_bf16_f32 v11, v12, v13
	ds_read2_b32 v[12:13], v41 offset0:148 offset1:181
	s_waitcnt lgkmcnt(0)
	v_pk_mul_f32 v[12:13], v[8:9], v[12:13] op_sel_hi:[0,1]
	v_cvt_pk_bf16_f32 v12, v12, v13
	ds_read2_b32 v[14:15], v41 offset0:214 offset1:247
	s_waitcnt lgkmcnt(0)
	v_pk_mul_f32 v[8:9], v[8:9], v[14:15] op_sel_hi:[0,1]
	v_cvt_pk_bf16_f32 v13, v8, v9
	v_ashrrev_i32_e32 v8, 31, v7
	v_mul_lo_u32 v14, s14, v8
	v_mul_lo_u32 v15, s15, v7
	v_mad_u64_u32 v[8:9], s[22:23], s14, v7, 0
	v_add3_u32 v9, v9, v14, v15
	v_lshl_add_u64 v[8:9], v[8:9], 1, v[2:3]
	global_store_dwordx4 v[8:9], v[10:13], off
	s_cbranch_vccnz .LBB0_1910
	global_load_dword v6, v[4:5], off offset:96
	s_waitcnt vmcnt(0)
	s_branch .LBB0_1910

; #define LAS __attribute__((address_space(3)))
; #define LDS_WAIT() asm volatile("s_waitcnt lgkmcnt(0)" ::: "memory")
; __device__ __forceinline__ unsigned cvt_pk_bf16(float lo, float hi) { const f32x2 v = {lo, hi}; unsigned r = __builtin_bit_cast(unsigned, __builtin_convertvector(v, bf16x2_t)); asm volatile("" : "+v"(r)); return r; }
; __device__ __forceinline__ void tr_item(const float* W, int ldn, int k0, int n0, const float* ks, const float* ns, bf16_t* WT, size_t dld, int rbase, int rstride, int dcol0, LAS float* scr, int lane) {
;     ...
;     for (int j = 0; j < 4; ++j) { const int n = (lane >> 3) + 8 * j; const LAS float* s = scr + (8 * c) * 33 + n; const float sc = ns ? ns[n] : 1.0f;
;         u32x4 o; o.x = cvt_pk_bf16(s[0 * 33] * sc, s[1 * 33] * sc); o.y = cvt_pk_bf16(s[2 * 33] * sc, s[3 * 33] * sc); o.z = cvt_pk_bf16(s[4 * 33] * sc, s[5 * 33] * sc); o.w = cvt_pk_bf16(s[6 * 33] * sc, s[7 * 33] * sc);
;         *(u32x4*)(WT + (size_t)(rbase + rstride * n) * dld + dcol0 + k0 + 8 * c) = o; }
;     LDS_WAIT(); asm volatile("" ::: "memory");
.LBB0_2001:
	ds_read2_b32 v[4:5], v41 offset0:24 offset1:57
	s_addk_i32 s4, 0x500
	s_add_i32 s58, s58, 0xa000
	s_cmp_lt_i32 s4, s51
	s_waitcnt lgkmcnt(0)
	v_pk_mul_f32 v[4:5], v[6:7], v[4:5] op_sel_hi:[0,1]
	v_cvt_pk_bf16_f32 v8, v4, v5
	ds_read2_b32 v[4:5], v41 offset0:90 offset1:123
	s_waitcnt lgkmcnt(0)
	v_pk_mul_f32 v[4:5], v[6:7], v[4:5] op_sel_hi:[0,1]
	v_cvt_pk_bf16_f32 v9, v4, v5
	ds_read2_b32 v[4:5], v41 offset0:156 offset1:189
	s_waitcnt lgkmcnt(0)
	v_pk_mul_f32 v[4:5], v[6:7], v[4:5] op_sel_hi:[0,1]
	v_cvt_pk_bf16_f32 v10, v4, v5
	ds_read2_b32 v[4:5], v41 offset0:222 offset1:255
	s_waitcnt lgkmcnt(0)
	v_pk_mul_f32 v[4:5], v[6:7], v[4:5] op_sel_hi:[0,1]
	v_cvt_pk_bf16_f32 v11, v4, v5
	v_add_u32_e32 v4, s2, v7
	v_ashrrev_i32_e32 v5, 31, v4
	v_mul_lo_u32 v6, s14, v5
	v_mul_lo_u32 v7, s15, v4
	v_mad_u64_u32 v[4:5], s[2:3], s14, v4, 0
	v_add3_u32 v5, v5, v6, v7
	v_lshl_add_u64 v[2:3], v[4:5], 1, v[2:3]
	global_store_dwordx4 v[2:3], v[8:11], off
	s_waitcnt lgkmcnt(0)
	s_cbranch_scc0 .LBB0_1962

; #define LAS __attribute__((address_space(3)))
; #define LDS_WAIT() asm volatile("s_waitcnt lgkmcnt(0)" ::: "memory")
; __device__ __forceinline__ unsigned cvt_pk_bf16(float lo, float hi) { const f32x2 v = {lo, hi}; unsigned r = __builtin_bit_cast(unsigned, __builtin_convertvector(v, bf16x2_t)); asm volatile("" : "+v"(r)); return r; }
; __device__ __forceinline__ void tr_item(const float* W, int ldn, int k0, int n0, const float* ks, const float* ns, bf16_t* WT, size_t dld, int rbase, int rstride, int dcol0, LAS float* scr, int lane) {
;     ...
;     const int c = lane & 7;
; #pragma unroll
;     for (int j = 0; j < 4; ++j) { const int n = (lane >> 3) + 8 * j; const LAS float* s = scr + (8 * c) * 33 + n; const float sc = ns ? ns[n] : 1.0f;
;         u32x4 o; o.x = cvt_pk_bf16(s[0 * 33] * sc, s[1 * 33] * sc); o.y = cvt_pk_bf16(s[2 * 33] * sc, s[3 * 33] * sc); o.z = cvt_pk_bf16(s[4 * 33] * sc, s[5 * 33] * sc); o.w = cvt_pk_bf16(s[6 * 33] * sc, s[7 * 33] * sc);
;         *(u32x4*)(WT + (size_t)(rbase + rstride * n) * dld + dcol0 + k0 + 8 * c) = o; }
;     LDS_WAIT(); asm volatile("" ::: "memory");
.LBB0_2041:
	ds_read2_b32 v[10:11], v41 offset1:33
	s_lshl_b64 s[2:3], s[24:25], 1
	s_add_u32 s22, s10, s2
	s_addc_u32 s23, s11, s3
	s_lshl_b64 s[2:3], s[26:27], 1
	s_waitcnt lgkmcnt(0)
	v_pk_mul_f32 v[10:11], v[8:9], v[10:11] op_sel_hi:[0,1]
	v_cvt_pk_bf16_f32 v10, v10, v11
	ds_read2_b32 v[12:13], v41 offset0:66 offset1:99
	v_mul_lo_u32 v7, s59, v34
	s_add_u32 s2, s22, s2
	v_add_u32_e32 v7, v7, v37
	s_addc_u32 s3, s23, s3
	s_waitcnt lgkmcnt(0)
	v_pk_mul_f32 v[12:13], v[8:9], v[12:13] op_sel_hi:[0,1]
	v_cvt_pk_bf16_f32 v11, v12, v13
	ds_read2_b32 v[12:13], v41 offset0:132 offset1:165
	v_lshl_add_u64 v[2:3], s[2:3], 0, v[0:1]
	s_and_b64 vcc, exec, s[6:7]
	s_waitcnt lgkmcnt(0)
	v_pk_mul_f32 v[12:13], v[8:9], v[12:13] op_sel_hi:[0,1]
	v_cvt_pk_bf16_f32 v12, v12, v13
	ds_read2_b32 v[14:15], v41 offset0:198 offset1:231
	s_waitcnt lgkmcnt(0)
	v_pk_mul_f32 v[8:9], v[8:9], v[14:15] op_sel_hi:[0,1]
	v_cvt_pk_bf16_f32 v13, v8, v9
	v_ashrrev_i32_e32 v8, 31, v7
	v_mul_lo_u32 v14, s14, v8
	v_mul_lo_u32 v15, s15, v7
	v_mad_u64_u32 v[8:9], s[2:3], s14, v7, 0
	v_add3_u32 v9, v9, v14, v15
	v_lshl_add_u64 v[8:9], v[8:9], 1, v[2:3]
	global_store_dwordx4 v[8:9], v[10:13], off
	s_cbranch_vccnz .LBB0_2043
	global_load_dword v6, v[4:5], off offset:32
	s_waitcnt vmcnt(0)
.LBB0_2043:
	ds_read2_b32 v[8:9], v41 offset0:8 offset1:41
	s_lshl_b32 s2, s59, 3
	s_and_b64 vcc, exec, s[6:7]
	s_waitcnt lgkmcnt(0)
	v_pk_mul_f32 v[8:9], v[6:7], v[8:9] op_sel_hi:[0,1]
	v_cvt_pk_bf16_f32 v8, v8, v9
	ds_read2_b32 v[10:11], v41 offset0:74 offset1:107
	s_waitcnt lgkmcnt(0)
	v_pk_mul_f32 v[10:11], v[6:7], v[10:11] op_sel_hi:[0,1]
	v_cvt_pk_bf16_f32 v9, v10, v11
	ds_read2_b32 v[10:11], v41 offset0:140 offset1:173
	s_waitcnt lgkmcnt(0)
	v_pk_mul_f32 v[10:11], v[6:7], v[10:11] op_sel_hi:[0,1]
	v_cvt_pk_bf16_f32 v10, v10, v11
	ds_read2_b32 v[12:13], v41 offset0:206 offset1:239
	s_waitcnt lgkmcnt(0)
	v_pk_mul_f32 v[12:13], v[6:7], v[12:13] op_sel_hi:[0,1]
	v_add_u32_e32 v7, s2, v7
	v_ashrrev_i32_e32 v6, 31, v7
	v_cvt_pk_bf16_f32 v11, v12, v13
	v_mul_lo_u32 v6, s14, v6
	v_mul_lo_u32 v14, s15, v7
	v_mad_u64_u32 v[12:13], s[22:23], s14, v7, 0
	v_add3_u32 v13, v13, v6, v14
	v_lshl_add_u64 v[12:13], v[12:13], 1, v[2:3]
	global_store_dwordx4 v[12:13], v[8:11], off
	v_mov_b32_e32 v6, 1.0
	s_nop 0
	v_mov_b32_e32 v8, 1.0
	s_cbranch_vccnz .LBB0_2045
	global_load_dword v8, v[4:5], off offset:64
	s_waitcnt vmcnt(0)
